# EpiProj regenerated: rstd reads hoisted, bpermute transpose software-pipelined one row-pair ahead (counted lgkmcnt), paired coalesced stores
# speedup vs baseline: 1.0007x; 1.0007x over previous
.LBB0_492:
	v_lshrrev_b32_e32 v160, 2, v213
	v_and_b32_e32 v161, 3, v213
	v_lshlrev_b32_e32 v162, 6, v161
	v_lshl_add_u32 v162, v160, 2, v162
	s_lshl_b32 s4, s65, 8
	s_add_i32 s4, s4, s47
	s_andn2_b64 vcc, exec, s[40:41]
	v_add_u32_e32 v149, s4, v160
	s_lshl_b32 s4, s53, 8
	s_or_b32 s4, s4, s48
	v_lshl_add_u32 v142, v161, 3, s4
	s_lshl_b32 s4, s58, 10
	s_add_i32 s4, s51, s4
	v_lshl_add_u32 v154, v144, 2, s4
	ds_read_b32 v164, v154
	ds_read_b32 v166, v154 offset:64
	ds_read_b32 v168, v154 offset:128
	ds_read_b32 v170, v154 offset:192
	ds_read_b32 v172, v154 offset:512
	ds_read_b32 v174, v154 offset:576
	ds_read_b32 v176, v154 offset:640
	ds_read_b32 v178, v154 offset:704
	v_ashrrev_i32_e32 v143, 31, v142
	v_mov_b64_e32 v[140:141], s[16:17]
	v_lshlrev_b64 v[142:143], 1, v[142:143]
	s_mov_b64 s[30:31], -1
	s_waitcnt lgkmcnt(0)
	v_pk_mul_f32 v[126:127], v[126:127], v[164:165] op_sel_hi:[1,0]
	v_pk_mul_f32 v[128:129], v[128:129], v[164:165] op_sel_hi:[1,0]
	v_pk_mul_f32 v[122:123], v[122:123], v[164:165] op_sel_hi:[1,0]
	v_pk_mul_f32 v[124:125], v[124:125], v[164:165] op_sel_hi:[1,0]
	v_cvt_pk_bf16_f32 v180, v126, v127
	v_cvt_pk_bf16_f32 v181, v128, v129
	v_cvt_pk_bf16_f32 v182, v122, v123
	v_cvt_pk_bf16_f32 v183, v124, v125
	v_pk_mul_f32 v[114:115], v[114:115], v[164:165] op_sel_hi:[1,0]
	v_pk_mul_f32 v[116:117], v[116:117], v[164:165] op_sel_hi:[1,0]
	v_pk_mul_f32 v[106:107], v[106:107], v[164:165] op_sel_hi:[1,0]
	v_pk_mul_f32 v[108:109], v[108:109], v[164:165] op_sel_hi:[1,0]
	v_cvt_pk_bf16_f32 v184, v114, v115
	v_cvt_pk_bf16_f32 v185, v116, v117
	v_cvt_pk_bf16_f32 v186, v106, v107
	v_cvt_pk_bf16_f32 v187, v108, v109
	ds_bpermute_b32 v180, v162, v180
	ds_bpermute_b32 v181, v162, v181
	ds_bpermute_b32 v182, v162, v182
	ds_bpermute_b32 v183, v162, v183
	ds_bpermute_b32 v184, v162, v184
	ds_bpermute_b32 v185, v162, v185
	ds_bpermute_b32 v186, v162, v186
	ds_bpermute_b32 v187, v162, v187
	v_mad_i64_i32 v[196:197], s[4:5], v149, s11, v[140:141]
	v_lshl_add_u64 v[196:197], v[196:197], 0, v[142:143]
	v_pk_mul_f32 v[118:119], v[118:119], v[166:167] op_sel_hi:[1,0]
	v_pk_mul_f32 v[120:121], v[120:121], v[166:167] op_sel_hi:[1,0]
	v_pk_mul_f32 v[110:111], v[110:111], v[166:167] op_sel_hi:[1,0]
	v_pk_mul_f32 v[112:113], v[112:113], v[166:167] op_sel_hi:[1,0]
	v_cvt_pk_bf16_f32 v188, v118, v119
	v_cvt_pk_bf16_f32 v189, v120, v121
	v_cvt_pk_bf16_f32 v190, v110, v111
	v_cvt_pk_bf16_f32 v191, v112, v113
	v_pk_mul_f32 v[98:99], v[98:99], v[166:167] op_sel_hi:[1,0]
	v_pk_mul_f32 v[100:101], v[100:101], v[166:167] op_sel_hi:[1,0]
	v_pk_mul_f32 v[90:91], v[90:91], v[166:167] op_sel_hi:[1,0]
	v_pk_mul_f32 v[92:93], v[92:93], v[166:167] op_sel_hi:[1,0]
	v_cvt_pk_bf16_f32 v192, v98, v99
	v_cvt_pk_bf16_f32 v193, v100, v101
	v_cvt_pk_bf16_f32 v194, v90, v91
	v_cvt_pk_bf16_f32 v195, v92, v93
	ds_bpermute_b32 v188, v162, v188
	ds_bpermute_b32 v189, v162, v189
	ds_bpermute_b32 v190, v162, v190
	ds_bpermute_b32 v191, v162, v191
	ds_bpermute_b32 v192, v162, v192
	ds_bpermute_b32 v193, v162, v193
	ds_bpermute_b32 v194, v162, v194
	ds_bpermute_b32 v195, v162, v195
	v_add_u32_e32 v200, 16, v149
	v_mad_i64_i32 v[198:199], s[4:5], v200, s11, v[140:141]
	v_lshl_add_u64 v[198:199], v[198:199], 0, v[142:143]
	s_waitcnt lgkmcnt(8)
	global_store_dwordx4 v[196:197], v[180:183], off
	global_store_dwordx4 v[196:197], v[184:187], off offset:256
	v_pk_mul_f32 v[102:103], v[102:103], v[168:169] op_sel_hi:[1,0]
	v_pk_mul_f32 v[104:105], v[104:105], v[168:169] op_sel_hi:[1,0]
	v_pk_mul_f32 v[94:95], v[94:95], v[168:169] op_sel_hi:[1,0]
	v_pk_mul_f32 v[96:97], v[96:97], v[168:169] op_sel_hi:[1,0]
	v_cvt_pk_bf16_f32 v180, v102, v103
	v_cvt_pk_bf16_f32 v181, v104, v105
	v_cvt_pk_bf16_f32 v182, v94, v95
	v_cvt_pk_bf16_f32 v183, v96, v97
	v_pk_mul_f32 v[82:83], v[82:83], v[168:169] op_sel_hi:[1,0]
	v_pk_mul_f32 v[84:85], v[84:85], v[168:169] op_sel_hi:[1,0]
	v_pk_mul_f32 v[74:75], v[74:75], v[168:169] op_sel_hi:[1,0]
	v_pk_mul_f32 v[76:77], v[76:77], v[168:169] op_sel_hi:[1,0]
	v_cvt_pk_bf16_f32 v184, v82, v83
	v_cvt_pk_bf16_f32 v185, v84, v85
	v_cvt_pk_bf16_f32 v186, v74, v75
	v_cvt_pk_bf16_f32 v187, v76, v77
	ds_bpermute_b32 v180, v162, v180
	ds_bpermute_b32 v181, v162, v181
	ds_bpermute_b32 v182, v162, v182
	ds_bpermute_b32 v183, v162, v183
	ds_bpermute_b32 v184, v162, v184
	ds_bpermute_b32 v185, v162, v185
	ds_bpermute_b32 v186, v162, v186
	ds_bpermute_b32 v187, v162, v187
	v_add_u32_e32 v200, 32, v149
	v_mad_i64_i32 v[196:197], s[4:5], v200, s11, v[140:141]
	v_lshl_add_u64 v[196:197], v[196:197], 0, v[142:143]
	s_waitcnt lgkmcnt(8)
	global_store_dwordx4 v[198:199], v[188:191], off
	global_store_dwordx4 v[198:199], v[192:195], off offset:256
	v_pk_mul_f32 v[86:87], v[86:87], v[170:171] op_sel_hi:[1,0]
	v_pk_mul_f32 v[88:89], v[88:89], v[170:171] op_sel_hi:[1,0]
	v_pk_mul_f32 v[78:79], v[78:79], v[170:171] op_sel_hi:[1,0]
	v_pk_mul_f32 v[80:81], v[80:81], v[170:171] op_sel_hi:[1,0]
	v_cvt_pk_bf16_f32 v188, v86, v87
	v_cvt_pk_bf16_f32 v189, v88, v89
	v_cvt_pk_bf16_f32 v190, v78, v79
	v_cvt_pk_bf16_f32 v191, v80, v81
	v_pk_mul_f32 v[70:71], v[70:71], v[170:171] op_sel_hi:[1,0]
	v_pk_mul_f32 v[72:73], v[72:73], v[170:171] op_sel_hi:[1,0]
	v_pk_mul_f32 v[66:67], v[66:67], v[170:171] op_sel_hi:[1,0]
	v_pk_mul_f32 v[68:69], v[68:69], v[170:171] op_sel_hi:[1,0]
	v_cvt_pk_bf16_f32 v192, v70, v71
	v_cvt_pk_bf16_f32 v193, v72, v73
	v_cvt_pk_bf16_f32 v194, v66, v67
	v_cvt_pk_bf16_f32 v195, v68, v69
	ds_bpermute_b32 v188, v162, v188
	ds_bpermute_b32 v189, v162, v189
	ds_bpermute_b32 v190, v162, v190
	ds_bpermute_b32 v191, v162, v191
	ds_bpermute_b32 v192, v162, v192
	ds_bpermute_b32 v193, v162, v193
	ds_bpermute_b32 v194, v162, v194
	ds_bpermute_b32 v195, v162, v195
	v_add_u32_e32 v200, 48, v149
	v_mad_i64_i32 v[198:199], s[4:5], v200, s11, v[140:141]
	v_lshl_add_u64 v[198:199], v[198:199], 0, v[142:143]
	s_waitcnt lgkmcnt(8)
	global_store_dwordx4 v[196:197], v[180:183], off
	global_store_dwordx4 v[196:197], v[184:187], off offset:256
	v_pk_mul_f32 v[62:63], v[62:63], v[172:173] op_sel_hi:[1,0]
	v_pk_mul_f32 v[64:65], v[64:65], v[172:173] op_sel_hi:[1,0]
	v_pk_mul_f32 v[58:59], v[58:59], v[172:173] op_sel_hi:[1,0]
	v_pk_mul_f32 v[60:61], v[60:61], v[172:173] op_sel_hi:[1,0]
	v_cvt_pk_bf16_f32 v180, v62, v63
	v_cvt_pk_bf16_f32 v181, v64, v65
	v_cvt_pk_bf16_f32 v182, v58, v59
	v_cvt_pk_bf16_f32 v183, v60, v61
	v_pk_mul_f32 v[50:51], v[50:51], v[172:173] op_sel_hi:[1,0]
	v_pk_mul_f32 v[52:53], v[52:53], v[172:173] op_sel_hi:[1,0]
	v_pk_mul_f32 v[42:43], v[42:43], v[172:173] op_sel_hi:[1,0]
	v_pk_mul_f32 v[44:45], v[44:45], v[172:173] op_sel_hi:[1,0]
	v_cvt_pk_bf16_f32 v184, v50, v51
	v_cvt_pk_bf16_f32 v185, v52, v53
	v_cvt_pk_bf16_f32 v186, v42, v43
	v_cvt_pk_bf16_f32 v187, v44, v45
	ds_bpermute_b32 v180, v162, v180
	ds_bpermute_b32 v181, v162, v181
	ds_bpermute_b32 v182, v162, v182
	ds_bpermute_b32 v183, v162, v183
	ds_bpermute_b32 v184, v162, v184
	ds_bpermute_b32 v185, v162, v185
	ds_bpermute_b32 v186, v162, v186
	ds_bpermute_b32 v187, v162, v187
	v_add_u32_e32 v200, 128, v149
	v_mad_i64_i32 v[196:197], s[4:5], v200, s11, v[140:141]
	v_lshl_add_u64 v[196:197], v[196:197], 0, v[142:143]
	s_waitcnt lgkmcnt(8)
	global_store_dwordx4 v[198:199], v[188:191], off
	global_store_dwordx4 v[198:199], v[192:195], off offset:256
	v_pk_mul_f32 v[54:55], v[54:55], v[174:175] op_sel_hi:[1,0]
	v_pk_mul_f32 v[56:57], v[56:57], v[174:175] op_sel_hi:[1,0]
	v_pk_mul_f32 v[46:47], v[46:47], v[174:175] op_sel_hi:[1,0]
	v_pk_mul_f32 v[48:49], v[48:49], v[174:175] op_sel_hi:[1,0]
	v_cvt_pk_bf16_f32 v188, v54, v55
	v_cvt_pk_bf16_f32 v189, v56, v57
	v_cvt_pk_bf16_f32 v190, v46, v47
	v_cvt_pk_bf16_f32 v191, v48, v49
	v_pk_mul_f32 v[34:35], v[34:35], v[174:175] op_sel_hi:[1,0]
	v_pk_mul_f32 v[36:37], v[36:37], v[174:175] op_sel_hi:[1,0]
	v_pk_mul_f32 v[26:27], v[26:27], v[174:175] op_sel_hi:[1,0]
	v_pk_mul_f32 v[28:29], v[28:29], v[174:175] op_sel_hi:[1,0]
	v_cvt_pk_bf16_f32 v192, v34, v35
	v_cvt_pk_bf16_f32 v193, v36, v37
	v_cvt_pk_bf16_f32 v194, v26, v27
	v_cvt_pk_bf16_f32 v195, v28, v29
	ds_bpermute_b32 v188, v162, v188
	ds_bpermute_b32 v189, v162, v189
	ds_bpermute_b32 v190, v162, v190
	ds_bpermute_b32 v191, v162, v191
	ds_bpermute_b32 v192, v162, v192
	ds_bpermute_b32 v193, v162, v193
	ds_bpermute_b32 v194, v162, v194
	ds_bpermute_b32 v195, v162, v195
	v_add_u32_e32 v200, 144, v149
	v_mad_i64_i32 v[198:199], s[4:5], v200, s11, v[140:141]
	v_lshl_add_u64 v[198:199], v[198:199], 0, v[142:143]
	s_waitcnt lgkmcnt(8)
	global_store_dwordx4 v[196:197], v[180:183], off
	global_store_dwordx4 v[196:197], v[184:187], off offset:256
	v_pk_mul_f32 v[38:39], v[38:39], v[176:177] op_sel_hi:[1,0]
	v_pk_mul_f32 v[40:41], v[40:41], v[176:177] op_sel_hi:[1,0]
	v_pk_mul_f32 v[30:31], v[30:31], v[176:177] op_sel_hi:[1,0]
	v_pk_mul_f32 v[32:33], v[32:33], v[176:177] op_sel_hi:[1,0]
	v_cvt_pk_bf16_f32 v180, v38, v39
	v_cvt_pk_bf16_f32 v181, v40, v41
	v_cvt_pk_bf16_f32 v182, v30, v31
	v_cvt_pk_bf16_f32 v183, v32, v33
	v_pk_mul_f32 v[18:19], v[18:19], v[176:177] op_sel_hi:[1,0]
	v_pk_mul_f32 v[20:21], v[20:21], v[176:177] op_sel_hi:[1,0]
	v_pk_mul_f32 v[10:11], v[10:11], v[176:177] op_sel_hi:[1,0]
	v_pk_mul_f32 v[12:13], v[12:13], v[176:177] op_sel_hi:[1,0]
	v_cvt_pk_bf16_f32 v184, v18, v19
	v_cvt_pk_bf16_f32 v185, v20, v21
	v_cvt_pk_bf16_f32 v186, v10, v11
	v_cvt_pk_bf16_f32 v187, v12, v13
	ds_bpermute_b32 v180, v162, v180
	ds_bpermute_b32 v181, v162, v181
	ds_bpermute_b32 v182, v162, v182
	ds_bpermute_b32 v183, v162, v183
	ds_bpermute_b32 v184, v162, v184
	ds_bpermute_b32 v185, v162, v185
	ds_bpermute_b32 v186, v162, v186
	ds_bpermute_b32 v187, v162, v187
	v_add_u32_e32 v200, 160, v149
	v_mad_i64_i32 v[196:197], s[4:5], v200, s11, v[140:141]
	v_lshl_add_u64 v[196:197], v[196:197], 0, v[142:143]
	s_waitcnt lgkmcnt(8)
	global_store_dwordx4 v[198:199], v[188:191], off
	global_store_dwordx4 v[198:199], v[192:195], off offset:256
	v_pk_mul_f32 v[22:23], v[22:23], v[178:179] op_sel_hi:[1,0]
	v_pk_mul_f32 v[24:25], v[24:25], v[178:179] op_sel_hi:[1,0]
	v_pk_mul_f32 v[14:15], v[14:15], v[178:179] op_sel_hi:[1,0]
	v_pk_mul_f32 v[16:17], v[16:17], v[178:179] op_sel_hi:[1,0]
	v_cvt_pk_bf16_f32 v188, v22, v23
	v_cvt_pk_bf16_f32 v189, v24, v25
	v_cvt_pk_bf16_f32 v190, v14, v15
	v_cvt_pk_bf16_f32 v191, v16, v17
	v_pk_mul_f32 v[6:7], v[6:7], v[178:179] op_sel_hi:[1,0]
	v_pk_mul_f32 v[8:9], v[8:9], v[178:179] op_sel_hi:[1,0]
	v_pk_mul_f32 v[2:3], v[2:3], v[178:179] op_sel_hi:[1,0]
	v_pk_mul_f32 v[4:5], v[4:5], v[178:179] op_sel_hi:[1,0]
	v_cvt_pk_bf16_f32 v192, v6, v7
	v_cvt_pk_bf16_f32 v193, v8, v9
	v_cvt_pk_bf16_f32 v194, v2, v3
	v_cvt_pk_bf16_f32 v195, v4, v5
	ds_bpermute_b32 v188, v162, v188
	ds_bpermute_b32 v189, v162, v189
	ds_bpermute_b32 v190, v162, v190
	ds_bpermute_b32 v191, v162, v191
	ds_bpermute_b32 v192, v162, v192
	ds_bpermute_b32 v193, v162, v193
	ds_bpermute_b32 v194, v162, v194
	ds_bpermute_b32 v195, v162, v195
	v_add_u32_e32 v200, 176, v149
	v_mad_i64_i32 v[198:199], s[4:5], v200, s11, v[140:141]
	v_lshl_add_u64 v[198:199], v[198:199], 0, v[142:143]
	s_waitcnt lgkmcnt(8)
	global_store_dwordx4 v[196:197], v[180:183], off
	global_store_dwordx4 v[196:197], v[184:187], off offset:256
	s_waitcnt lgkmcnt(0)
	global_store_dwordx4 v[198:199], v[188:191], off
	global_store_dwordx4 v[198:199], v[192:195], off offset:256
	s_cbranch_vccnz .LBB0_485
	s_andn2_b64 vcc, exec, s[14:15]
	s_cbranch_vccnz .LBB0_484
	s_barrier
	s_branch .LBB0_484
